# DSA up-projection weight fragment loads lane-coalesced with ds_bpermute back to the MFMA operand layout
# baseline (speedup 1.0000x reference)
;     ...
;     { const int c16 = lane & 15, quad = lane >> 4, hh = wid >> 1;
;       bf16x8 wf[4][4]; u16 zv[4][4];
; #pragma unroll
;       for (int i = 0; i < 4; ++i) { const int d = ((wid & 1) * 4 + i) * 16 + c16; const u16* wp = p.WuvT + ((size_t)hh * 128 + d) * 128 + quad * 8;
; #pragma unroll
;           for (int ks = 0; ks < 4; ++ks) wf[i][ks] = *(const bf16x8*)(wp + ks * 32);
; #pragma unroll
;           for (int j = 0; j < 4; ++j) zv[i][j] = p.proj[(size_t)(bl * SEQ + t0 + 4 * (quad & 1) + j) * NP + C_BZ + hh * 128 + d]; }
.LBB0_961:
	s_or_b64 exec, exec, s[0:1]
	s_lshl_b32 s26, s37, 12
	s_waitcnt vmcnt(2)
	v_lshlrev_b32_e32 v70, 2, v128
	s_add_i32 s0, s30, s26
	v_and_or_b32 v0, v70, 4, s0
	s_and_b32 s0, s59, 0xffffff80
	v_mul_i32_i24_e32 v0, 0x5800, v0
	s_ashr_i32 s20, s59, 7
	s_ashr_i32 s1, s0, 31
	s_waitcnt lgkmcnt(0)
	v_lshl_add_u64 v[4:5], s[14:15], 0, v[0:1]
	v_and_or_b32 v0, s59, 64, v127
	s_ashr_i32 s21, s20, 31
	v_bfe_u32 v226, v163, 2, 4
	v_and_or_b32 v226, s59, 64, v226
	v_lshlrev_b32_e32 v6, 8, v226
	v_and_b32_e32 v226, 3, v163
	v_lshlrev_b32_e32 v226, 4, v226
	v_mov_b32_e32 v227, 0
	v_lshlrev_b32_e32 v0, 1, v0
	v_lshl_add_u64 v[4:5], s[0:1], 1, v[4:5]
	s_lshl_b64 s[22:23], s[20:21], 15
	v_lshl_add_u64 v[4:5], v[4:5], 0, v[0:1]
	s_movk_i32 s21, 0x1000
	v_add_co_u32_e32 v20, vcc, s21, v4
	s_movk_i32 s21, 0x6000
	s_nop 0
	v_addc_co_u32_e32 v21, vcc, 0, v5, vcc
	v_add_co_u32_e32 v24, vcc, s21, v4
	s_mov_b64 s[24:25], 0x1400
	s_nop 0
	v_addc_co_u32_e32 v25, vcc, 0, v5, vcc
	s_mov_b32 s21, 0xc000
	v_lshl_add_u64 v[18:19], v[4:5], 0, s[24:25]
	s_mov_b64 s[24:25], 0x6c00
	v_add_co_u32_e32 v72, vcc, s21, v4
	v_lshl_add_u64 v[22:23], v[4:5], 0, s[24:25]
	s_mov_b64 s[24:25], 0xc400
	v_addc_co_u32_e32 v73, vcc, 0, v5, vcc
	s_mov_b32 s21, 0x11000
	v_mov_b32_e32 v125, v1
	v_lshl_add_u64 v[92:93], v[4:5], 0, s[24:25]
	s_mov_b64 s[24:25], 0x11c00
	s_waitcnt vmcnt(1)
	v_add_co_u32_e32 v76, vcc, s21, v4
	v_lshl_add_u64 v[2:3], s[10:11], 0, v[226:227]
	v_mov_b32_e32 v7, v1
	v_lshl_add_u64 v[94:95], v[4:5], 0, s[24:25]
	v_addc_co_u32_e32 v77, vcc, 0, v5, vcc
	v_or_b32_e32 v4, 0x1000, v6
	v_mov_b32_e32 v5, v1
	v_lshl_add_u64 v[8:9], v[2:3], 0, v[6:7]
	v_lshl_add_u64 v[4:5], v[2:3], 0, v[4:5]
	v_lshl_add_u64 v[8:9], v[8:9], 0, s[22:23]
	v_lshl_add_u64 v[4:5], v[4:5], 0, s[22:23]
	global_load_dwordx4 v[26:29], v[8:9], off
	global_load_dwordx4 v[30:33], v[8:9], off offset:64
	global_load_dwordx4 v[66:69], v[8:9], off offset:128
	global_load_dwordx4 v[88:91], v[8:9], off offset:192
	global_load_dwordx4 v[50:53], v[4:5], off
	global_load_dwordx4 v[54:57], v[4:5], off offset:64
	global_load_dwordx4 v[58:61], v[4:5], off offset:128
	global_load_dwordx4 v[62:65], v[4:5], off offset:192
	v_or_b32_e32 v4, 0x2000, v6
	v_mov_b32_e32 v5, v1
	v_lshl_add_u64 v[4:5], v[2:3], 0, v[4:5]
	v_lshl_add_u64 v[4:5], v[4:5], 0, s[22:23]
	global_load_dwordx4 v[34:37], v[4:5], off
	global_load_dwordx4 v[38:41], v[4:5], off offset:64
	global_load_dwordx4 v[42:45], v[4:5], off offset:128
	global_load_dwordx4 v[46:49], v[4:5], off offset:192
	v_or_b32_e32 v4, 0x3000, v6
	v_mov_b32_e32 v5, v1
	v_lshl_add_u64 v[2:3], v[2:3], 0, v[4:5]
	v_lshl_add_u64 v[14:15], v[2:3], 0, s[22:23]
	global_load_dwordx4 v[2:5], v[14:15], off
	global_load_dwordx4 v[6:9], v[14:15], off offset:64
	global_load_dwordx4 v[10:13], v[14:15], off offset:128
	s_nop 0
	global_load_dwordx4 v[14:17], v[14:15], off offset:192
	s_nop 0
	global_load_ushort v71, v[20:21], off offset:1024
	global_load_ushort v86, v[24:25], off offset:3072
	global_load_ushort v83, v[18:19], off offset:32
	global_load_ushort v82, v[22:23], off offset:32
	global_load_ushort v79, v[18:19], off offset:64
	global_load_ushort v78, v[22:23], off offset:64
	global_load_ushort v74, v[22:23], off offset:96
	global_load_ushort v75, v[18:19], off offset:96
	global_load_ushort v85, v[72:73], off offset:1024
	global_load_ushort v84, v[76:77], off offset:3072
	global_load_ushort v81, v[92:93], off offset:32
	global_load_ushort v80, v[94:95], off offset:32
	s_nop 0
	global_load_ushort v77, v[92:93], off offset:64
	global_load_ushort v76, v[94:95], off offset:64
	global_load_ushort v72, v[94:95], off offset:96
	global_load_ushort v73, v[92:93], off offset:96
	v_lshlrev_b32_e32 v18, 14, v163
	s_lshl_b32 s20, s20, 8
	v_and_b32_e32 v18, 0x1c000, v18
	s_add_i32 s20, s20, 0
	v_add3_u32 v87, s20, v18, v126
	s_barrier
; #define LAS __attribute__((address_space(3)))
; __device__ __forceinline__ float bf2f(u16 b) { return __uint_as_float(((unsigned)b) << 16); }
; __device__ __forceinline__ u16 f2bf(float f) { return (u16)(cvtpk(f, 0.f) & 0xffffu); }
; __device__ __forceinline__ float siluf_(float x) { return x * sigmoidf_(x); }
;     ...
;       __syncthreads();
;       if (sm & 32) {
;           LAS u16* olat = (LAS u16*)(lds + (c16 & 7) * 16384);
;           bf16x8 af[4];
; #pragma unroll
;           for (int ks = 0; ks < 4; ++ks) af[ks] = *(const LAS bf16x8*)(olat + hh * 128 + ks * 32 + quad * 8);
; #pragma unroll
;           for (int i = 0; i < 4; ++i) {
;               const int d = ((wid & 1) * 4 + i) * 16 + c16;
;               f32x4 a = {0.f, 0.f, 0.f, 0.f};
; #pragma unroll
;               for (int ks = 0; ks < 4; ++ks) a = __builtin_amdgcn_mfma_f32_16x16x32_bf16(af[ks], wf[i][ks], a, 0, 0, 0);
;               if (quad < 2 && sm == 63) {
; #pragma unroll
;                   for (int j = 0; j < 4; ++j) { const size_t grow = (size_t)(bl * SEQ + t0 + 4 * quad + j);
;                       p.ybuf[((size_t)1 * MG + grow) * 512 + hh * 128 + d] = f2bf(a[j] * siluf_(bf2f(zv[i][j]))); }
	v_and_b32_e32 v224, 15, v163
	v_bfe_u32 v225, v163, 4, 2
	v_lshl_or_b32 v224, v224, 2, v225
	v_lshlrev_b32_e32 v224, 2, v224
	s_waitcnt vmcnt(16)
	ds_bpermute_b32 v26, v224, v26
	ds_bpermute_b32 v27, v224, v27
	ds_bpermute_b32 v28, v224, v28
	ds_bpermute_b32 v29, v224, v29
	ds_bpermute_b32 v30, v224, v30
	ds_bpermute_b32 v31, v224, v31
	ds_bpermute_b32 v32, v224, v32
	ds_bpermute_b32 v33, v224, v33
	ds_bpermute_b32 v66, v224, v66
	ds_bpermute_b32 v67, v224, v67
	ds_bpermute_b32 v68, v224, v68
	ds_bpermute_b32 v69, v224, v69
	ds_bpermute_b32 v88, v224, v88
	ds_bpermute_b32 v89, v224, v89
	ds_bpermute_b32 v90, v224, v90
	s_waitcnt lgkmcnt(7)
	ds_bpermute_b32 v91, v224, v91
	ds_bpermute_b32 v50, v224, v50
	ds_bpermute_b32 v51, v224, v51
	ds_bpermute_b32 v52, v224, v52
	ds_bpermute_b32 v53, v224, v53
	ds_bpermute_b32 v54, v224, v54
	ds_bpermute_b32 v55, v224, v55
	ds_bpermute_b32 v56, v224, v56
	s_waitcnt lgkmcnt(7)
	ds_bpermute_b32 v57, v224, v57
	ds_bpermute_b32 v58, v224, v58
	ds_bpermute_b32 v59, v224, v59
	ds_bpermute_b32 v60, v224, v60
	ds_bpermute_b32 v61, v224, v61
	ds_bpermute_b32 v62, v224, v62
	ds_bpermute_b32 v63, v224, v63
	ds_bpermute_b32 v64, v224, v64
	s_waitcnt lgkmcnt(7)
	ds_bpermute_b32 v65, v224, v65
	ds_bpermute_b32 v34, v224, v34
	ds_bpermute_b32 v35, v224, v35
	ds_bpermute_b32 v36, v224, v36
	ds_bpermute_b32 v37, v224, v37
	ds_bpermute_b32 v38, v224, v38
	ds_bpermute_b32 v39, v224, v39
	ds_bpermute_b32 v40, v224, v40
	s_waitcnt lgkmcnt(7)
	ds_bpermute_b32 v41, v224, v41
	ds_bpermute_b32 v42, v224, v42
	ds_bpermute_b32 v43, v224, v43
	ds_bpermute_b32 v44, v224, v44
	ds_bpermute_b32 v45, v224, v45
	ds_bpermute_b32 v46, v224, v46
	ds_bpermute_b32 v47, v224, v47
	ds_bpermute_b32 v48, v224, v48
	s_waitcnt lgkmcnt(7)
	ds_bpermute_b32 v49, v224, v49
	ds_bpermute_b32 v2, v224, v2
	ds_bpermute_b32 v3, v224, v3
	ds_bpermute_b32 v4, v224, v4
	ds_bpermute_b32 v5, v224, v5
	ds_bpermute_b32 v6, v224, v6
	ds_bpermute_b32 v7, v224, v7
	ds_bpermute_b32 v8, v224, v8
	s_waitcnt lgkmcnt(7)
	ds_bpermute_b32 v9, v224, v9
	ds_bpermute_b32 v10, v224, v10
	ds_bpermute_b32 v11, v224, v11
	ds_bpermute_b32 v12, v224, v12
	ds_bpermute_b32 v13, v224, v13
	ds_bpermute_b32 v14, v224, v14
	ds_bpermute_b32 v15, v224, v15
	ds_bpermute_b32 v16, v224, v16
	s_waitcnt lgkmcnt(7)
	ds_bpermute_b32 v17, v224, v17
	s_waitcnt lgkmcnt(0)
	ds_read_b128 v[18:21], v87
	ds_read_b128 v[22:25], v87 offset:64
	v_or_b32_e32 v70, s26, v70
	v_add_u32_e32 v70, s30, v70
	v_cmp_gt_u32_e64 s[38:39], 32, v163
	v_lshlrev_b32_e32 v70, 10, v70
	s_waitcnt vmcnt(31) lgkmcnt(1)
	v_mfma_f32_16x16x32_bf16 v[92:95], v[18:21], v[26:29], 0
	ds_read_b128 v[26:29], v87 offset:128
	s_waitcnt vmcnt(30) lgkmcnt(1)
	v_mfma_f32_16x16x32_bf16 v[92:95], v[22:25], v[30:33], v[92:95]
	ds_read_b128 v[30:33], v87 offset:192
	s_waitcnt vmcnt(29) lgkmcnt(1)
	v_mfma_f32_16x16x32_bf16 v[66:69], v[26:29], v[66:69], v[92:95]
	s_waitcnt vmcnt(28) lgkmcnt(0)
	v_mfma_f32_16x16x32_bf16 v[66:69], v[30:33], v[88:91], v[66:69]
	s_and_saveexec_b64 s[20:21], s[38:39]
	s_cbranch_execz .LBB0_963
	s_waitcnt vmcnt(15)
	v_lshlrev_b32_e32 v71, 16, v71
	v_mul_f32_e32 v87, 0xbfb8aa3b, v71
	v_exp_f32_e32 v87, v87
	s_mov_b32 s22, 0x1000000
	v_add_f32_e32 v87, 1.0, v87
	v_rcp_f32_e32 v87, v87
	s_nop 0
	v_mul_f32_e32 v71, v87, v71
	v_mul_f32_e32 v66, v71, v66
	v_mov_b32_e32 v71, v1
	v_lshl_add_u64 v[88:89], s[16:17], 0, v[70:71]
	v_lshl_add_u64 v[88:89], s[0:1], 1, v[88:89]
	v_lshl_add_u64 v[88:89], v[88:89], 0, v[0:1]
	v_add_co_u32_e32 v88, vcc, s22, v88
	v_cvt_pk_bf16_f32 v66, v66, v1
	s_nop 1
	v_addc_co_u32_e32 v89, vcc, 0, v89, vcc
	global_store_short v[88:89], v66, off
	s_waitcnt vmcnt(15)
	v_lshlrev_b32_e32 v66, 16, v86
	v_mul_f32_e32 v71, 0xbfb8aa3b, v66
	v_exp_f32_e32 v71, v71
	s_nop 0
	v_add_f32_e32 v71, 1.0, v71
	v_rcp_f32_e32 v71, v71
	s_nop 0
	v_mul_f32_e32 v66, v71, v66
	v_mul_f32_e32 v66, v66, v67
	v_cvt_pk_bf16_f32 v66, v66, v1
	global_store_short v[88:89], v66, off offset:1024
	s_waitcnt vmcnt(9)
	v_lshlrev_b32_e32 v66, 16, v85
	v_mul_f32_e32 v67, 0xbfb8aa3b, v66
	v_exp_f32_e32 v67, v67
	s_nop 0
	v_add_f32_e32 v67, 1.0, v67
	v_rcp_f32_e32 v67, v67
	s_nop 0
	v_mul_f32_e32 v66, v67, v66
	v_mul_f32_e32 v66, v66, v68
	v_cvt_pk_bf16_f32 v66, v66, v1
	global_store_short v[88:89], v66, off offset:2048
	s_waitcnt vmcnt(9)
	v_lshlrev_b32_e32 v66, 16, v84
	v_mul_f32_e32 v67, 0xbfb8aa3b, v66
	v_exp_f32_e32 v67, v67
	s_nop 0
	v_add_f32_e32 v67, 1.0, v67
	v_rcp_f32_e32 v67, v67
	s_nop 0
	v_mul_f32_e32 v66, v67, v66
	v_mul_f32_e32 v66, v66, v69
	v_cvt_pk_bf16_f32 v66, v66, v1
	global_store_short v[88:89], v66, off offset:3072
